# v19 + redundant pass-prologue workgroup barrier removed (tile loops end with a barrier after their last LDS reads)
# baseline (speedup 1.0000x reference)
; template <int PM> DI void attn_phase(const Params& p, int l, char* smem, int* s_item, int wv, int cidx) {
;     ...
;       __syncthreads();
;       {
;         const u16* base = p.P + (size_t)(Rb + trow) * INW + tch * 8;
; #pragma unroll
;         for (int j = 0; j < 2; ++j) {
;           kst[j] = *(const u32x4*)(base + (size_t)j * 32 * INW + koff);
;           vst[j] = *(const u32x4*)(base + (size_t)j * 32 * INW + voff);
;         }
; #pragma unroll
;         for (int j = 0; j < 2; ++j) {
;           *(u32x4*)(Kb0 + (trow + 32 * j) * 272 + tch * 16) = kst[j];
;           *(u32x4*)(Vb0 + (trow + 32 * j) * 320 + tch * 16) = vst[j];
;         }
;         const int R1 = (1 < nplain) ? Rb + 64 : Rb + 256 + local_t0 + 64 * (1 - nplain);
;         const u16* b1 = p.P + (size_t)(R1 + trow) * INW + tch * 8;
;         if (ntl > 1) {
; #pragma unroll
;           for (int j = 0; j < 2; ++j) {
;             kst[j] = *(const u32x4*)(b1 + (size_t)j * 32 * INW + koff);
;             vst[j] = *(const u32x4*)(b1 + (size_t)j * 32 * INW + voff);
;           }
;         }
.LBB0_418:
	global_load_dwordx4 v[180:183], v[210:211], off
	global_load_dwordx4 v[184:187], v[212:213], off
	global_load_dwordx4 v[188:191], v[214:215], off
	global_load_dwordx4 v[192:195], v[216:217], off
	v_readlane_b32 s0, v255, 1
	v_readlane_b32 s1, v255, 2
	v_add_u32_e32 v0, v196, v246
	v_add_u32_e32 v2, v196, v247
	s_andn2_b64 vcc, exec, s[0:1]
	s_waitcnt vmcnt(3)
	ds_write_b128 v0, v[180:183]
	s_waitcnt vmcnt(2)
	ds_write_b128 v2, v[184:187] offset:34816
	s_waitcnt vmcnt(1)
	ds_write_b128 v0, v[188:191] offset:8704
	s_waitcnt vmcnt(0)
	ds_write_b128 v2, v[192:195] offset:45056
	s_cbranch_vccnz .LBB0_420
	global_load_dwordx4 v[180:183], v[224:225], off
	global_load_dwordx4 v[184:187], v[222:223], off
	global_load_dwordx4 v[188:191], v[220:221], off
	global_load_dwordx4 v[192:195], v[218:219], off
